# scan: tree A-sum + prio; helper waves: prefetch landed in own registers, vmcnt drain moved off the chunk barrier, global_* ops
# baseline (speedup 1.0000x reference)
.Lscan_chunk:
	s_and_b32 s30, s33, 1
	s_mul_i32 s31, s30, 0xa000
	v_add_u32_e32 v94, s31, v0
	s_lshl_b32 s31, s30, 11
	v_add_u32_e32 v95, s31, v100
	v_add_u32_e32 v96, 0x400, v95
	s_lshl_b32 s31, s30, 12
	v_add_u32_e32 v97, s31, v98
	ds_read_b128 v[6:9], v94 offset:0
	ds_read_b128 v[10:13], v94 offset:16
	ds_read_b128 v[14:17], v94 offset:32
	ds_read_b128 v[18:21], v94 offset:48
	ds_read_b128 v[22:25], v94 offset:64
	ds_read2_b32 v[66:67], v95 offset0:0 offset1:16
	ds_read_b128 v[26:29], v94 offset:1280
	ds_read_b128 v[30:33], v94 offset:1296
	ds_read_b128 v[34:37], v94 offset:1312
	ds_read_b128 v[38:41], v94 offset:1328
	ds_read_b128 v[42:45], v94 offset:1344
	ds_read2_b32 v[68:69], v95 offset0:32 offset1:48
	s_waitcnt lgkmcnt(6)
	v_pk_mul_f32 v[70:71], v[2:3], v[6:7] op_sel_hi:[0,1]
	v_pk_mul_f32 v[72:73], v[2:3], v[8:9] op_sel:[1,0]
	v_pk_fma_f32 v[70:71], v[4:5], v[10:11], v[70:71] op_sel_hi:[0,1,1]
	v_pk_fma_f32 v[72:73], v[4:5], v[12:13], v[72:73] op_sel:[1,0,0]
	v_pk_add_f32 v[70:71], v[70:71], v[72:73]
	v_pk_mul_f32 v[76:77], v[22:23], v[66:67] op_sel_hi:[1,0]
	v_pk_mul_f32 v[92:93], v[24:25], v[66:67] op_sel_hi:[1,0]
	v_add_f32_dpp v74, v71, v70 row_mirror row_mask:0xf bank_mask:0xf bound_ctrl:1
	v_pk_fma_f32 v[76:77], v[2:3], v[14:15], v[76:77]
	v_pk_fma_f32 v[92:93], v[4:5], v[16:17], v[92:93]
	v_add_f32_dpp v74, v74, v74 row_half_mirror row_mask:0xf bank_mask:0xf bound_ctrl:1
	ds_read_b128 v[46:49], v94 offset:2560
	ds_read_b128 v[50:53], v94 offset:2576
	v_add_f32_dpp v74, v74, v74 quad_perm:[1,0,3,2] row_mask:0xf bank_mask:0xf bound_ctrl:1
	ds_read_b128 v[54:57], v94 offset:2592
	ds_read_b128 v[58:61], v94 offset:2608
	v_add_f32_dpp v74, v74, v74 quad_perm:[2,3,0,1] row_mask:0xf bank_mask:0xf bound_ctrl:1
	ds_read_b128 v[62:65], v94 offset:2624
	ds_write_b32 v97, v74 offset:0
	ds_read2_b32 v[132:133], v95 offset0:64 offset1:80
	v_mov_b32_dpp v74, v74 row_mirror row_mask:0xf bank_mask:0xc
	v_pk_fma_f32 v[2:3], v[18:19], v[74:75], v[76:77] op_sel_hi:[1,0,1]
	v_pk_fma_f32 v[4:5], v[20:21], v[74:75], v[92:93] op_sel_hi:[1,0,1]
	s_waitcnt lgkmcnt(8)
	v_pk_mul_f32 v[70:71], v[2:3], v[26:27] op_sel_hi:[0,1]
	v_pk_mul_f32 v[72:73], v[2:3], v[28:29] op_sel:[1,0]
	v_pk_fma_f32 v[70:71], v[4:5], v[30:31], v[70:71] op_sel_hi:[0,1,1]
	v_pk_fma_f32 v[72:73], v[4:5], v[32:33], v[72:73] op_sel:[1,0,0]
	v_pk_add_f32 v[70:71], v[70:71], v[72:73]
	v_pk_mul_f32 v[76:77], v[42:43], v[66:67] op_sel:[0,1]
	v_pk_mul_f32 v[92:93], v[44:45], v[66:67] op_sel:[0,1]
	v_add_f32_dpp v74, v71, v70 row_mirror row_mask:0xf bank_mask:0xf bound_ctrl:1
	v_pk_fma_f32 v[76:77], v[2:3], v[34:35], v[76:77]
	v_pk_fma_f32 v[92:93], v[4:5], v[36:37], v[92:93]
	v_add_f32_dpp v74, v74, v74 row_half_mirror row_mask:0xf bank_mask:0xf bound_ctrl:1
	ds_read_b128 v[6:9], v94 offset:3840
	ds_read_b128 v[10:13], v94 offset:3856
	v_add_f32_dpp v74, v74, v74 quad_perm:[1,0,3,2] row_mask:0xf bank_mask:0xf bound_ctrl:1
	ds_read_b128 v[14:17], v94 offset:3872
	ds_read_b128 v[18:21], v94 offset:3888
	v_add_f32_dpp v74, v74, v74 quad_perm:[2,3,0,1] row_mask:0xf bank_mask:0xf bound_ctrl:1
	ds_read_b128 v[22:25], v94 offset:3904
	ds_write_b32 v97, v74 offset:8
	v_mov_b32_dpp v74, v74 row_mirror row_mask:0xf bank_mask:0xc
	v_pk_fma_f32 v[2:3], v[38:39], v[74:75], v[76:77] op_sel_hi:[1,0,1]
	v_pk_fma_f32 v[4:5], v[40:41], v[74:75], v[92:93] op_sel_hi:[1,0,1]
	s_waitcnt lgkmcnt(8)
	v_pk_mul_f32 v[70:71], v[2:3], v[46:47] op_sel_hi:[0,1]
	v_pk_mul_f32 v[72:73], v[2:3], v[48:49] op_sel:[1,0]
	v_pk_fma_f32 v[70:71], v[4:5], v[50:51], v[70:71] op_sel_hi:[0,1,1]
	v_pk_fma_f32 v[72:73], v[4:5], v[52:53], v[72:73] op_sel:[1,0,0]
	v_pk_add_f32 v[70:71], v[70:71], v[72:73]
	v_pk_mul_f32 v[76:77], v[62:63], v[68:69] op_sel_hi:[1,0]
	v_pk_mul_f32 v[92:93], v[64:65], v[68:69] op_sel_hi:[1,0]
	v_add_f32_dpp v74, v71, v70 row_mirror row_mask:0xf bank_mask:0xf bound_ctrl:1
	v_pk_fma_f32 v[76:77], v[2:3], v[54:55], v[76:77]
	v_pk_fma_f32 v[92:93], v[4:5], v[56:57], v[92:93]
	v_add_f32_dpp v74, v74, v74 row_half_mirror row_mask:0xf bank_mask:0xf bound_ctrl:1
	ds_read_b128 v[26:29], v94 offset:5120
	ds_read_b128 v[30:33], v94 offset:5136
	v_add_f32_dpp v74, v74, v74 quad_perm:[1,0,3,2] row_mask:0xf bank_mask:0xf bound_ctrl:1
	ds_read_b128 v[34:37], v94 offset:5152
	ds_read_b128 v[38:41], v94 offset:5168
	v_add_f32_dpp v74, v74, v74 quad_perm:[2,3,0,1] row_mask:0xf bank_mask:0xf bound_ctrl:1
	ds_read_b128 v[42:45], v94 offset:5184
	ds_write_b32 v97, v74 offset:256
	ds_read2_b32 v[66:67], v95 offset0:96 offset1:112
	v_mov_b32_dpp v74, v74 row_mirror row_mask:0xf bank_mask:0xc
	v_pk_fma_f32 v[2:3], v[58:59], v[74:75], v[76:77] op_sel_hi:[1,0,1]
	v_pk_fma_f32 v[4:5], v[60:61], v[74:75], v[92:93] op_sel_hi:[1,0,1]
	s_waitcnt lgkmcnt(8)
	v_pk_mul_f32 v[70:71], v[2:3], v[6:7] op_sel_hi:[0,1]
	v_pk_mul_f32 v[72:73], v[2:3], v[8:9] op_sel:[1,0]
	v_pk_fma_f32 v[70:71], v[4:5], v[10:11], v[70:71] op_sel_hi:[0,1,1]
	v_pk_fma_f32 v[72:73], v[4:5], v[12:13], v[72:73] op_sel:[1,0,0]
	v_pk_add_f32 v[70:71], v[70:71], v[72:73]
	v_pk_mul_f32 v[76:77], v[22:23], v[68:69] op_sel:[0,1]
	v_pk_mul_f32 v[92:93], v[24:25], v[68:69] op_sel:[0,1]
	v_add_f32_dpp v74, v71, v70 row_mirror row_mask:0xf bank_mask:0xf bound_ctrl:1
	v_pk_fma_f32 v[76:77], v[2:3], v[14:15], v[76:77]
	v_pk_fma_f32 v[92:93], v[4:5], v[16:17], v[92:93]
	v_add_f32_dpp v74, v74, v74 row_half_mirror row_mask:0xf bank_mask:0xf bound_ctrl:1
	ds_read_b128 v[46:49], v94 offset:6400
	ds_read_b128 v[50:53], v94 offset:6416
	v_add_f32_dpp v74, v74, v74 quad_perm:[1,0,3,2] row_mask:0xf bank_mask:0xf bound_ctrl:1
	ds_read_b128 v[54:57], v94 offset:6432
	ds_read_b128 v[58:61], v94 offset:6448
	v_add_f32_dpp v74, v74, v74 quad_perm:[2,3,0,1] row_mask:0xf bank_mask:0xf bound_ctrl:1
	ds_read_b128 v[62:65], v94 offset:6464
	ds_write_b32 v97, v74 offset:264
	v_mov_b32_dpp v74, v74 row_mirror row_mask:0xf bank_mask:0xc
	v_pk_fma_f32 v[2:3], v[18:19], v[74:75], v[76:77] op_sel_hi:[1,0,1]
	v_pk_fma_f32 v[4:5], v[20:21], v[74:75], v[92:93] op_sel_hi:[1,0,1]
	s_waitcnt lgkmcnt(8)
	v_pk_mul_f32 v[70:71], v[2:3], v[26:27] op_sel_hi:[0,1]
	v_pk_mul_f32 v[72:73], v[2:3], v[28:29] op_sel:[1,0]
	v_pk_fma_f32 v[70:71], v[4:5], v[30:31], v[70:71] op_sel_hi:[0,1,1]
	v_pk_fma_f32 v[72:73], v[4:5], v[32:33], v[72:73] op_sel:[1,0,0]
	v_pk_add_f32 v[70:71], v[70:71], v[72:73]
	v_pk_mul_f32 v[76:77], v[42:43], v[132:133] op_sel_hi:[1,0]
	v_pk_mul_f32 v[92:93], v[44:45], v[132:133] op_sel_hi:[1,0]
	v_add_f32_dpp v74, v71, v70 row_mirror row_mask:0xf bank_mask:0xf bound_ctrl:1
	v_pk_fma_f32 v[76:77], v[2:3], v[34:35], v[76:77]
	v_pk_fma_f32 v[92:93], v[4:5], v[36:37], v[92:93]
	v_add_f32_dpp v74, v74, v74 row_half_mirror row_mask:0xf bank_mask:0xf bound_ctrl:1
	ds_read_b128 v[6:9], v94 offset:7680
	ds_read_b128 v[10:13], v94 offset:7696
	v_add_f32_dpp v74, v74, v74 quad_perm:[1,0,3,2] row_mask:0xf bank_mask:0xf bound_ctrl:1
	ds_read_b128 v[14:17], v94 offset:7712
	ds_read_b128 v[18:21], v94 offset:7728
	v_add_f32_dpp v74, v74, v74 quad_perm:[2,3,0,1] row_mask:0xf bank_mask:0xf bound_ctrl:1
	ds_read_b128 v[22:25], v94 offset:7744
	ds_write_b32 v97, v74 offset:512
	ds_read2_b32 v[68:69], v95 offset0:128 offset1:144
	v_mov_b32_dpp v74, v74 row_mirror row_mask:0xf bank_mask:0xc
	v_pk_fma_f32 v[2:3], v[38:39], v[74:75], v[76:77] op_sel_hi:[1,0,1]
	v_pk_fma_f32 v[4:5], v[40:41], v[74:75], v[92:93] op_sel_hi:[1,0,1]
	s_waitcnt lgkmcnt(8)
	v_pk_mul_f32 v[70:71], v[2:3], v[46:47] op_sel_hi:[0,1]
	v_pk_mul_f32 v[72:73], v[2:3], v[48:49] op_sel:[1,0]
	v_pk_fma_f32 v[70:71], v[4:5], v[50:51], v[70:71] op_sel_hi:[0,1,1]
	v_pk_fma_f32 v[72:73], v[4:5], v[52:53], v[72:73] op_sel:[1,0,0]
	v_pk_add_f32 v[70:71], v[70:71], v[72:73]
	v_pk_mul_f32 v[76:77], v[62:63], v[132:133] op_sel:[0,1]
	v_pk_mul_f32 v[92:93], v[64:65], v[132:133] op_sel:[0,1]
	v_add_f32_dpp v74, v71, v70 row_mirror row_mask:0xf bank_mask:0xf bound_ctrl:1
	v_pk_fma_f32 v[76:77], v[2:3], v[54:55], v[76:77]
	v_pk_fma_f32 v[92:93], v[4:5], v[56:57], v[92:93]
	v_add_f32_dpp v74, v74, v74 row_half_mirror row_mask:0xf bank_mask:0xf bound_ctrl:1
	ds_read_b128 v[26:29], v94 offset:8960
	ds_read_b128 v[30:33], v94 offset:8976
	v_add_f32_dpp v74, v74, v74 quad_perm:[1,0,3,2] row_mask:0xf bank_mask:0xf bound_ctrl:1
	ds_read_b128 v[34:37], v94 offset:8992
	ds_read_b128 v[38:41], v94 offset:9008
	v_add_f32_dpp v74, v74, v74 quad_perm:[2,3,0,1] row_mask:0xf bank_mask:0xf bound_ctrl:1
	ds_read_b128 v[42:45], v94 offset:9024
	ds_write_b32 v97, v74 offset:520
	v_mov_b32_dpp v74, v74 row_mirror row_mask:0xf bank_mask:0xc
	v_pk_fma_f32 v[2:3], v[58:59], v[74:75], v[76:77] op_sel_hi:[1,0,1]
	v_pk_fma_f32 v[4:5], v[60:61], v[74:75], v[92:93] op_sel_hi:[1,0,1]
	s_waitcnt lgkmcnt(8)
	v_pk_mul_f32 v[70:71], v[2:3], v[6:7] op_sel_hi:[0,1]
	v_pk_mul_f32 v[72:73], v[2:3], v[8:9] op_sel:[1,0]
	v_pk_fma_f32 v[70:71], v[4:5], v[10:11], v[70:71] op_sel_hi:[0,1,1]
	v_pk_fma_f32 v[72:73], v[4:5], v[12:13], v[72:73] op_sel:[1,0,0]
	v_pk_add_f32 v[70:71], v[70:71], v[72:73]
	v_pk_mul_f32 v[76:77], v[22:23], v[66:67] op_sel_hi:[1,0]
	v_pk_mul_f32 v[92:93], v[24:25], v[66:67] op_sel_hi:[1,0]
	v_add_f32_dpp v74, v71, v70 row_mirror row_mask:0xf bank_mask:0xf bound_ctrl:1
	v_pk_fma_f32 v[76:77], v[2:3], v[14:15], v[76:77]
	v_pk_fma_f32 v[92:93], v[4:5], v[16:17], v[92:93]
	v_add_f32_dpp v74, v74, v74 row_half_mirror row_mask:0xf bank_mask:0xf bound_ctrl:1
	ds_read_b128 v[46:49], v94 offset:10240
	ds_read_b128 v[50:53], v94 offset:10256
	v_add_f32_dpp v74, v74, v74 quad_perm:[1,0,3,2] row_mask:0xf bank_mask:0xf bound_ctrl:1
	ds_read_b128 v[54:57], v94 offset:10272
	ds_read_b128 v[58:61], v94 offset:10288
	v_add_f32_dpp v74, v74, v74 quad_perm:[2,3,0,1] row_mask:0xf bank_mask:0xf bound_ctrl:1
	ds_read_b128 v[62:65], v94 offset:10304
	ds_write_b32 v97, v74 offset:768
	ds_read2_b32 v[132:133], v95 offset0:160 offset1:176
	v_mov_b32_dpp v74, v74 row_mirror row_mask:0xf bank_mask:0xc
	v_pk_fma_f32 v[2:3], v[18:19], v[74:75], v[76:77] op_sel_hi:[1,0,1]
	v_pk_fma_f32 v[4:5], v[20:21], v[74:75], v[92:93] op_sel_hi:[1,0,1]
	s_waitcnt lgkmcnt(8)
	v_pk_mul_f32 v[70:71], v[2:3], v[26:27] op_sel_hi:[0,1]
	v_pk_mul_f32 v[72:73], v[2:3], v[28:29] op_sel:[1,0]
	v_pk_fma_f32 v[70:71], v[4:5], v[30:31], v[70:71] op_sel_hi:[0,1,1]
	v_pk_fma_f32 v[72:73], v[4:5], v[32:33], v[72:73] op_sel:[1,0,0]
	v_pk_add_f32 v[70:71], v[70:71], v[72:73]
	v_pk_mul_f32 v[76:77], v[42:43], v[66:67] op_sel:[0,1]
	v_pk_mul_f32 v[92:93], v[44:45], v[66:67] op_sel:[0,1]
	v_add_f32_dpp v74, v71, v70 row_mirror row_mask:0xf bank_mask:0xf bound_ctrl:1
	v_pk_fma_f32 v[76:77], v[2:3], v[34:35], v[76:77]
	v_pk_fma_f32 v[92:93], v[4:5], v[36:37], v[92:93]
	v_add_f32_dpp v74, v74, v74 row_half_mirror row_mask:0xf bank_mask:0xf bound_ctrl:1
	ds_read_b128 v[6:9], v94 offset:11520
	ds_read_b128 v[10:13], v94 offset:11536
	v_add_f32_dpp v74, v74, v74 quad_perm:[1,0,3,2] row_mask:0xf bank_mask:0xf bound_ctrl:1
	ds_read_b128 v[14:17], v94 offset:11552
	ds_read_b128 v[18:21], v94 offset:11568
	v_add_f32_dpp v74, v74, v74 quad_perm:[2,3,0,1] row_mask:0xf bank_mask:0xf bound_ctrl:1
	ds_read_b128 v[22:25], v94 offset:11584
	ds_write_b32 v97, v74 offset:776
	v_mov_b32_dpp v74, v74 row_mirror row_mask:0xf bank_mask:0xc
	v_pk_fma_f32 v[2:3], v[38:39], v[74:75], v[76:77] op_sel_hi:[1,0,1]
	v_pk_fma_f32 v[4:5], v[40:41], v[74:75], v[92:93] op_sel_hi:[1,0,1]
	s_waitcnt lgkmcnt(8)
	v_pk_mul_f32 v[70:71], v[2:3], v[46:47] op_sel_hi:[0,1]
	v_pk_mul_f32 v[72:73], v[2:3], v[48:49] op_sel:[1,0]
	v_pk_fma_f32 v[70:71], v[4:5], v[50:51], v[70:71] op_sel_hi:[0,1,1]
	v_pk_fma_f32 v[72:73], v[4:5], v[52:53], v[72:73] op_sel:[1,0,0]
	v_pk_add_f32 v[70:71], v[70:71], v[72:73]
	v_pk_mul_f32 v[76:77], v[62:63], v[68:69] op_sel_hi:[1,0]
	v_pk_mul_f32 v[92:93], v[64:65], v[68:69] op_sel_hi:[1,0]
	v_add_f32_dpp v74, v71, v70 row_mirror row_mask:0xf bank_mask:0xf bound_ctrl:1
	v_pk_fma_f32 v[76:77], v[2:3], v[54:55], v[76:77]
	v_pk_fma_f32 v[92:93], v[4:5], v[56:57], v[92:93]
	v_add_f32_dpp v74, v74, v74 row_half_mirror row_mask:0xf bank_mask:0xf bound_ctrl:1
	ds_read_b128 v[26:29], v94 offset:12800
	ds_read_b128 v[30:33], v94 offset:12816
	v_add_f32_dpp v74, v74, v74 quad_perm:[1,0,3,2] row_mask:0xf bank_mask:0xf bound_ctrl:1
	ds_read_b128 v[34:37], v94 offset:12832
	ds_read_b128 v[38:41], v94 offset:12848
	v_add_f32_dpp v74, v74, v74 quad_perm:[2,3,0,1] row_mask:0xf bank_mask:0xf bound_ctrl:1
	ds_read_b128 v[42:45], v94 offset:12864
	ds_write_b32 v97, v74 offset:1024
	ds_read2_b32 v[66:67], v95 offset0:192 offset1:208
	v_mov_b32_dpp v74, v74 row_mirror row_mask:0xf bank_mask:0xc
	v_pk_fma_f32 v[2:3], v[58:59], v[74:75], v[76:77] op_sel_hi:[1,0,1]
	v_pk_fma_f32 v[4:5], v[60:61], v[74:75], v[92:93] op_sel_hi:[1,0,1]
	s_waitcnt lgkmcnt(8)
	v_pk_mul_f32 v[70:71], v[2:3], v[6:7] op_sel_hi:[0,1]
	v_pk_mul_f32 v[72:73], v[2:3], v[8:9] op_sel:[1,0]
	v_pk_fma_f32 v[70:71], v[4:5], v[10:11], v[70:71] op_sel_hi:[0,1,1]
	v_pk_fma_f32 v[72:73], v[4:5], v[12:13], v[72:73] op_sel:[1,0,0]
	v_pk_add_f32 v[70:71], v[70:71], v[72:73]
	v_pk_mul_f32 v[76:77], v[22:23], v[68:69] op_sel:[0,1]
	v_pk_mul_f32 v[92:93], v[24:25], v[68:69] op_sel:[0,1]
	v_add_f32_dpp v74, v71, v70 row_mirror row_mask:0xf bank_mask:0xf bound_ctrl:1
	v_pk_fma_f32 v[76:77], v[2:3], v[14:15], v[76:77]
	v_pk_fma_f32 v[92:93], v[4:5], v[16:17], v[92:93]
	v_add_f32_dpp v74, v74, v74 row_half_mirror row_mask:0xf bank_mask:0xf bound_ctrl:1
	ds_read_b128 v[46:49], v94 offset:14080
	ds_read_b128 v[50:53], v94 offset:14096
	v_add_f32_dpp v74, v74, v74 quad_perm:[1,0,3,2] row_mask:0xf bank_mask:0xf bound_ctrl:1
	ds_read_b128 v[54:57], v94 offset:14112
	ds_read_b128 v[58:61], v94 offset:14128
	v_add_f32_dpp v74, v74, v74 quad_perm:[2,3,0,1] row_mask:0xf bank_mask:0xf bound_ctrl:1
	ds_read_b128 v[62:65], v94 offset:14144
	ds_write_b32 v97, v74 offset:1032
	v_mov_b32_dpp v74, v74 row_mirror row_mask:0xf bank_mask:0xc
	v_pk_fma_f32 v[2:3], v[18:19], v[74:75], v[76:77] op_sel_hi:[1,0,1]
	v_pk_fma_f32 v[4:5], v[20:21], v[74:75], v[92:93] op_sel_hi:[1,0,1]
	s_waitcnt lgkmcnt(8)
	v_pk_mul_f32 v[70:71], v[2:3], v[26:27] op_sel_hi:[0,1]
	v_pk_mul_f32 v[72:73], v[2:3], v[28:29] op_sel:[1,0]
	v_pk_fma_f32 v[70:71], v[4:5], v[30:31], v[70:71] op_sel_hi:[0,1,1]
	v_pk_fma_f32 v[72:73], v[4:5], v[32:33], v[72:73] op_sel:[1,0,0]
	v_pk_add_f32 v[70:71], v[70:71], v[72:73]
	v_pk_mul_f32 v[76:77], v[42:43], v[132:133] op_sel_hi:[1,0]
	v_pk_mul_f32 v[92:93], v[44:45], v[132:133] op_sel_hi:[1,0]
	v_add_f32_dpp v74, v71, v70 row_mirror row_mask:0xf bank_mask:0xf bound_ctrl:1
	v_pk_fma_f32 v[76:77], v[2:3], v[34:35], v[76:77]
	v_pk_fma_f32 v[92:93], v[4:5], v[36:37], v[92:93]
	v_add_f32_dpp v74, v74, v74 row_half_mirror row_mask:0xf bank_mask:0xf bound_ctrl:1
	ds_read_b128 v[6:9], v94 offset:15360
	ds_read_b128 v[10:13], v94 offset:15376
	v_add_f32_dpp v74, v74, v74 quad_perm:[1,0,3,2] row_mask:0xf bank_mask:0xf bound_ctrl:1
	ds_read_b128 v[14:17], v94 offset:15392
	ds_read_b128 v[18:21], v94 offset:15408
	v_add_f32_dpp v74, v74, v74 quad_perm:[2,3,0,1] row_mask:0xf bank_mask:0xf bound_ctrl:1
	ds_read_b128 v[22:25], v94 offset:15424
	ds_write_b32 v97, v74 offset:1280
	ds_read2_b32 v[68:69], v95 offset0:224 offset1:240
	v_mov_b32_dpp v74, v74 row_mirror row_mask:0xf bank_mask:0xc
	v_pk_fma_f32 v[2:3], v[38:39], v[74:75], v[76:77] op_sel_hi:[1,0,1]
	v_pk_fma_f32 v[4:5], v[40:41], v[74:75], v[92:93] op_sel_hi:[1,0,1]
	s_waitcnt lgkmcnt(8)
	v_pk_mul_f32 v[70:71], v[2:3], v[46:47] op_sel_hi:[0,1]
	v_pk_mul_f32 v[72:73], v[2:3], v[48:49] op_sel:[1,0]
	v_pk_fma_f32 v[70:71], v[4:5], v[50:51], v[70:71] op_sel_hi:[0,1,1]
	v_pk_fma_f32 v[72:73], v[4:5], v[52:53], v[72:73] op_sel:[1,0,0]
	v_pk_add_f32 v[70:71], v[70:71], v[72:73]
	v_pk_mul_f32 v[76:77], v[62:63], v[132:133] op_sel:[0,1]
	v_pk_mul_f32 v[92:93], v[64:65], v[132:133] op_sel:[0,1]
	v_add_f32_dpp v74, v71, v70 row_mirror row_mask:0xf bank_mask:0xf bound_ctrl:1
	v_pk_fma_f32 v[76:77], v[2:3], v[54:55], v[76:77]
	v_pk_fma_f32 v[92:93], v[4:5], v[56:57], v[92:93]
	v_add_f32_dpp v74, v74, v74 row_half_mirror row_mask:0xf bank_mask:0xf bound_ctrl:1
	ds_read_b128 v[26:29], v94 offset:16640
	ds_read_b128 v[30:33], v94 offset:16656
	v_add_f32_dpp v74, v74, v74 quad_perm:[1,0,3,2] row_mask:0xf bank_mask:0xf bound_ctrl:1
	ds_read_b128 v[34:37], v94 offset:16672
	ds_read_b128 v[38:41], v94 offset:16688
	v_add_f32_dpp v74, v74, v74 quad_perm:[2,3,0,1] row_mask:0xf bank_mask:0xf bound_ctrl:1
	ds_read_b128 v[42:45], v94 offset:16704
	ds_write_b32 v97, v74 offset:1288
	v_mov_b32_dpp v74, v74 row_mirror row_mask:0xf bank_mask:0xc
	v_pk_fma_f32 v[2:3], v[58:59], v[74:75], v[76:77] op_sel_hi:[1,0,1]
	v_pk_fma_f32 v[4:5], v[60:61], v[74:75], v[92:93] op_sel_hi:[1,0,1]
	s_waitcnt lgkmcnt(8)
	v_pk_mul_f32 v[70:71], v[2:3], v[6:7] op_sel_hi:[0,1]
	v_pk_mul_f32 v[72:73], v[2:3], v[8:9] op_sel:[1,0]
	v_pk_fma_f32 v[70:71], v[4:5], v[10:11], v[70:71] op_sel_hi:[0,1,1]
	v_pk_fma_f32 v[72:73], v[4:5], v[12:13], v[72:73] op_sel:[1,0,0]
	v_pk_add_f32 v[70:71], v[70:71], v[72:73]
	v_pk_mul_f32 v[76:77], v[22:23], v[66:67] op_sel_hi:[1,0]
	v_pk_mul_f32 v[92:93], v[24:25], v[66:67] op_sel_hi:[1,0]
	v_add_f32_dpp v74, v71, v70 row_mirror row_mask:0xf bank_mask:0xf bound_ctrl:1
	v_pk_fma_f32 v[76:77], v[2:3], v[14:15], v[76:77]
	v_pk_fma_f32 v[92:93], v[4:5], v[16:17], v[92:93]
	v_add_f32_dpp v74, v74, v74 row_half_mirror row_mask:0xf bank_mask:0xf bound_ctrl:1
	ds_read_b128 v[46:49], v94 offset:17920
	ds_read_b128 v[50:53], v94 offset:17936
	v_add_f32_dpp v74, v74, v74 quad_perm:[1,0,3,2] row_mask:0xf bank_mask:0xf bound_ctrl:1
	ds_read_b128 v[54:57], v94 offset:17952
	ds_read_b128 v[58:61], v94 offset:17968
	v_add_f32_dpp v74, v74, v74 quad_perm:[2,3,0,1] row_mask:0xf bank_mask:0xf bound_ctrl:1
	ds_read_b128 v[62:65], v94 offset:17984
	ds_write_b32 v97, v74 offset:1536
	ds_read2_b32 v[132:133], v96 offset0:0 offset1:16
	v_mov_b32_dpp v74, v74 row_mirror row_mask:0xf bank_mask:0xc
	v_pk_fma_f32 v[2:3], v[18:19], v[74:75], v[76:77] op_sel_hi:[1,0,1]
	v_pk_fma_f32 v[4:5], v[20:21], v[74:75], v[92:93] op_sel_hi:[1,0,1]
	s_waitcnt lgkmcnt(8)
	v_pk_mul_f32 v[70:71], v[2:3], v[26:27] op_sel_hi:[0,1]
	v_pk_mul_f32 v[72:73], v[2:3], v[28:29] op_sel:[1,0]
	v_pk_fma_f32 v[70:71], v[4:5], v[30:31], v[70:71] op_sel_hi:[0,1,1]
	v_pk_fma_f32 v[72:73], v[4:5], v[32:33], v[72:73] op_sel:[1,0,0]
	v_pk_add_f32 v[70:71], v[70:71], v[72:73]
	v_pk_mul_f32 v[76:77], v[42:43], v[66:67] op_sel:[0,1]
	v_pk_mul_f32 v[92:93], v[44:45], v[66:67] op_sel:[0,1]
	v_add_f32_dpp v74, v71, v70 row_mirror row_mask:0xf bank_mask:0xf bound_ctrl:1
	v_pk_fma_f32 v[76:77], v[2:3], v[34:35], v[76:77]
	v_pk_fma_f32 v[92:93], v[4:5], v[36:37], v[92:93]
	v_add_f32_dpp v74, v74, v74 row_half_mirror row_mask:0xf bank_mask:0xf bound_ctrl:1
	ds_read_b128 v[6:9], v94 offset:19200
	ds_read_b128 v[10:13], v94 offset:19216
	v_add_f32_dpp v74, v74, v74 quad_perm:[1,0,3,2] row_mask:0xf bank_mask:0xf bound_ctrl:1
	ds_read_b128 v[14:17], v94 offset:19232
	ds_read_b128 v[18:21], v94 offset:19248
	v_add_f32_dpp v74, v74, v74 quad_perm:[2,3,0,1] row_mask:0xf bank_mask:0xf bound_ctrl:1
	ds_read_b128 v[22:25], v94 offset:19264
	ds_write_b32 v97, v74 offset:1544
	v_mov_b32_dpp v74, v74 row_mirror row_mask:0xf bank_mask:0xc
	v_pk_fma_f32 v[2:3], v[38:39], v[74:75], v[76:77] op_sel_hi:[1,0,1]
	v_pk_fma_f32 v[4:5], v[40:41], v[74:75], v[92:93] op_sel_hi:[1,0,1]
	s_waitcnt lgkmcnt(8)
	v_pk_mul_f32 v[70:71], v[2:3], v[46:47] op_sel_hi:[0,1]
	v_pk_mul_f32 v[72:73], v[2:3], v[48:49] op_sel:[1,0]
	v_pk_fma_f32 v[70:71], v[4:5], v[50:51], v[70:71] op_sel_hi:[0,1,1]
	v_pk_fma_f32 v[72:73], v[4:5], v[52:53], v[72:73] op_sel:[1,0,0]
	v_pk_add_f32 v[70:71], v[70:71], v[72:73]
	v_pk_mul_f32 v[76:77], v[62:63], v[68:69] op_sel_hi:[1,0]
	v_pk_mul_f32 v[92:93], v[64:65], v[68:69] op_sel_hi:[1,0]
	v_add_f32_dpp v74, v71, v70 row_mirror row_mask:0xf bank_mask:0xf bound_ctrl:1
	v_pk_fma_f32 v[76:77], v[2:3], v[54:55], v[76:77]
	v_pk_fma_f32 v[92:93], v[4:5], v[56:57], v[92:93]
	v_add_f32_dpp v74, v74, v74 row_half_mirror row_mask:0xf bank_mask:0xf bound_ctrl:1
	ds_read_b128 v[26:29], v94 offset:20480
	ds_read_b128 v[30:33], v94 offset:20496
	v_add_f32_dpp v74, v74, v74 quad_perm:[1,0,3,2] row_mask:0xf bank_mask:0xf bound_ctrl:1
	ds_read_b128 v[34:37], v94 offset:20512
	ds_read_b128 v[38:41], v94 offset:20528
	v_add_f32_dpp v74, v74, v74 quad_perm:[2,3,0,1] row_mask:0xf bank_mask:0xf bound_ctrl:1
	ds_read_b128 v[42:45], v94 offset:20544
	ds_write_b32 v97, v74 offset:1792
	ds_read2_b32 v[66:67], v96 offset0:32 offset1:48
	v_mov_b32_dpp v74, v74 row_mirror row_mask:0xf bank_mask:0xc
	v_pk_fma_f32 v[2:3], v[58:59], v[74:75], v[76:77] op_sel_hi:[1,0,1]
	v_pk_fma_f32 v[4:5], v[60:61], v[74:75], v[92:93] op_sel_hi:[1,0,1]
	s_waitcnt lgkmcnt(8)
	v_pk_mul_f32 v[70:71], v[2:3], v[6:7] op_sel_hi:[0,1]
	v_pk_mul_f32 v[72:73], v[2:3], v[8:9] op_sel:[1,0]
	v_pk_fma_f32 v[70:71], v[4:5], v[10:11], v[70:71] op_sel_hi:[0,1,1]
	v_pk_fma_f32 v[72:73], v[4:5], v[12:13], v[72:73] op_sel:[1,0,0]
	v_pk_add_f32 v[70:71], v[70:71], v[72:73]
	v_pk_mul_f32 v[76:77], v[22:23], v[68:69] op_sel:[0,1]
	v_pk_mul_f32 v[92:93], v[24:25], v[68:69] op_sel:[0,1]
	v_add_f32_dpp v74, v71, v70 row_mirror row_mask:0xf bank_mask:0xf bound_ctrl:1
	v_pk_fma_f32 v[76:77], v[2:3], v[14:15], v[76:77]
	v_pk_fma_f32 v[92:93], v[4:5], v[16:17], v[92:93]
	v_add_f32_dpp v74, v74, v74 row_half_mirror row_mask:0xf bank_mask:0xf bound_ctrl:1
	ds_read_b128 v[46:49], v94 offset:21760
	ds_read_b128 v[50:53], v94 offset:21776
	v_add_f32_dpp v74, v74, v74 quad_perm:[1,0,3,2] row_mask:0xf bank_mask:0xf bound_ctrl:1
	ds_read_b128 v[54:57], v94 offset:21792
	ds_read_b128 v[58:61], v94 offset:21808
	v_add_f32_dpp v74, v74, v74 quad_perm:[2,3,0,1] row_mask:0xf bank_mask:0xf bound_ctrl:1
	ds_read_b128 v[62:65], v94 offset:21824
	ds_write_b32 v97, v74 offset:1800
	v_mov_b32_dpp v74, v74 row_mirror row_mask:0xf bank_mask:0xc
	v_pk_fma_f32 v[2:3], v[18:19], v[74:75], v[76:77] op_sel_hi:[1,0,1]
	v_pk_fma_f32 v[4:5], v[20:21], v[74:75], v[92:93] op_sel_hi:[1,0,1]
	s_waitcnt lgkmcnt(8)
	v_pk_mul_f32 v[70:71], v[2:3], v[26:27] op_sel_hi:[0,1]
	v_pk_mul_f32 v[72:73], v[2:3], v[28:29] op_sel:[1,0]
	v_pk_fma_f32 v[70:71], v[4:5], v[30:31], v[70:71] op_sel_hi:[0,1,1]
	v_pk_fma_f32 v[72:73], v[4:5], v[32:33], v[72:73] op_sel:[1,0,0]
	v_pk_add_f32 v[70:71], v[70:71], v[72:73]
	v_pk_mul_f32 v[76:77], v[42:43], v[132:133] op_sel_hi:[1,0]
	v_pk_mul_f32 v[92:93], v[44:45], v[132:133] op_sel_hi:[1,0]
	v_add_f32_dpp v74, v71, v70 row_mirror row_mask:0xf bank_mask:0xf bound_ctrl:1
	v_pk_fma_f32 v[76:77], v[2:3], v[34:35], v[76:77]
	v_pk_fma_f32 v[92:93], v[4:5], v[36:37], v[92:93]
	v_add_f32_dpp v74, v74, v74 row_half_mirror row_mask:0xf bank_mask:0xf bound_ctrl:1
	ds_read_b128 v[6:9], v94 offset:23040
	ds_read_b128 v[10:13], v94 offset:23056
	v_add_f32_dpp v74, v74, v74 quad_perm:[1,0,3,2] row_mask:0xf bank_mask:0xf bound_ctrl:1
	ds_read_b128 v[14:17], v94 offset:23072
	ds_read_b128 v[18:21], v94 offset:23088
	v_add_f32_dpp v74, v74, v74 quad_perm:[2,3,0,1] row_mask:0xf bank_mask:0xf bound_ctrl:1
	ds_read_b128 v[22:25], v94 offset:23104
	ds_write_b32 v97, v74 offset:2048
	ds_read2_b32 v[68:69], v96 offset0:64 offset1:80
	v_mov_b32_dpp v74, v74 row_mirror row_mask:0xf bank_mask:0xc
	v_pk_fma_f32 v[2:3], v[38:39], v[74:75], v[76:77] op_sel_hi:[1,0,1]
	v_pk_fma_f32 v[4:5], v[40:41], v[74:75], v[92:93] op_sel_hi:[1,0,1]
	s_waitcnt lgkmcnt(8)
	v_pk_mul_f32 v[70:71], v[2:3], v[46:47] op_sel_hi:[0,1]
	v_pk_mul_f32 v[72:73], v[2:3], v[48:49] op_sel:[1,0]
	v_pk_fma_f32 v[70:71], v[4:5], v[50:51], v[70:71] op_sel_hi:[0,1,1]
	v_pk_fma_f32 v[72:73], v[4:5], v[52:53], v[72:73] op_sel:[1,0,0]
	v_pk_add_f32 v[70:71], v[70:71], v[72:73]
	v_pk_mul_f32 v[76:77], v[62:63], v[132:133] op_sel:[0,1]
	v_pk_mul_f32 v[92:93], v[64:65], v[132:133] op_sel:[0,1]
	v_add_f32_dpp v74, v71, v70 row_mirror row_mask:0xf bank_mask:0xf bound_ctrl:1
	v_pk_fma_f32 v[76:77], v[2:3], v[54:55], v[76:77]
	v_pk_fma_f32 v[92:93], v[4:5], v[56:57], v[92:93]
	v_add_f32_dpp v74, v74, v74 row_half_mirror row_mask:0xf bank_mask:0xf bound_ctrl:1
	ds_read_b128 v[26:29], v94 offset:24320
	ds_read_b128 v[30:33], v94 offset:24336
	v_add_f32_dpp v74, v74, v74 quad_perm:[1,0,3,2] row_mask:0xf bank_mask:0xf bound_ctrl:1
	ds_read_b128 v[34:37], v94 offset:24352
	ds_read_b128 v[38:41], v94 offset:24368
	v_add_f32_dpp v74, v74, v74 quad_perm:[2,3,0,1] row_mask:0xf bank_mask:0xf bound_ctrl:1
	ds_read_b128 v[42:45], v94 offset:24384
	ds_write_b32 v97, v74 offset:2056
	v_mov_b32_dpp v74, v74 row_mirror row_mask:0xf bank_mask:0xc
	v_pk_fma_f32 v[2:3], v[58:59], v[74:75], v[76:77] op_sel_hi:[1,0,1]
	v_pk_fma_f32 v[4:5], v[60:61], v[74:75], v[92:93] op_sel_hi:[1,0,1]
	s_waitcnt lgkmcnt(8)
	v_pk_mul_f32 v[70:71], v[2:3], v[6:7] op_sel_hi:[0,1]
	v_pk_mul_f32 v[72:73], v[2:3], v[8:9] op_sel:[1,0]
	v_pk_fma_f32 v[70:71], v[4:5], v[10:11], v[70:71] op_sel_hi:[0,1,1]
	v_pk_fma_f32 v[72:73], v[4:5], v[12:13], v[72:73] op_sel:[1,0,0]
	v_pk_add_f32 v[70:71], v[70:71], v[72:73]
	v_pk_mul_f32 v[76:77], v[22:23], v[66:67] op_sel_hi:[1,0]
	v_pk_mul_f32 v[92:93], v[24:25], v[66:67] op_sel_hi:[1,0]
	v_add_f32_dpp v74, v71, v70 row_mirror row_mask:0xf bank_mask:0xf bound_ctrl:1
	v_pk_fma_f32 v[76:77], v[2:3], v[14:15], v[76:77]
	v_pk_fma_f32 v[92:93], v[4:5], v[16:17], v[92:93]
	v_add_f32_dpp v74, v74, v74 row_half_mirror row_mask:0xf bank_mask:0xf bound_ctrl:1
	ds_read_b128 v[46:49], v94 offset:25600
	ds_read_b128 v[50:53], v94 offset:25616
	v_add_f32_dpp v74, v74, v74 quad_perm:[1,0,3,2] row_mask:0xf bank_mask:0xf bound_ctrl:1
	ds_read_b128 v[54:57], v94 offset:25632
	ds_read_b128 v[58:61], v94 offset:25648
	v_add_f32_dpp v74, v74, v74 quad_perm:[2,3,0,1] row_mask:0xf bank_mask:0xf bound_ctrl:1
	ds_read_b128 v[62:65], v94 offset:25664
	ds_write_b32 v97, v74 offset:2304
	ds_read2_b32 v[132:133], v96 offset0:96 offset1:112
	v_mov_b32_dpp v74, v74 row_mirror row_mask:0xf bank_mask:0xc
	v_pk_fma_f32 v[2:3], v[18:19], v[74:75], v[76:77] op_sel_hi:[1,0,1]
	v_pk_fma_f32 v[4:5], v[20:21], v[74:75], v[92:93] op_sel_hi:[1,0,1]
	s_waitcnt lgkmcnt(8)
	v_pk_mul_f32 v[70:71], v[2:3], v[26:27] op_sel_hi:[0,1]
	v_pk_mul_f32 v[72:73], v[2:3], v[28:29] op_sel:[1,0]
	v_pk_fma_f32 v[70:71], v[4:5], v[30:31], v[70:71] op_sel_hi:[0,1,1]
	v_pk_fma_f32 v[72:73], v[4:5], v[32:33], v[72:73] op_sel:[1,0,0]
	v_pk_add_f32 v[70:71], v[70:71], v[72:73]
	v_pk_mul_f32 v[76:77], v[42:43], v[66:67] op_sel:[0,1]
	v_pk_mul_f32 v[92:93], v[44:45], v[66:67] op_sel:[0,1]
	v_add_f32_dpp v74, v71, v70 row_mirror row_mask:0xf bank_mask:0xf bound_ctrl:1
	v_pk_fma_f32 v[76:77], v[2:3], v[34:35], v[76:77]
	v_pk_fma_f32 v[92:93], v[4:5], v[36:37], v[92:93]
	v_add_f32_dpp v74, v74, v74 row_half_mirror row_mask:0xf bank_mask:0xf bound_ctrl:1
	ds_read_b128 v[6:9], v94 offset:26880
	ds_read_b128 v[10:13], v94 offset:26896
	v_add_f32_dpp v74, v74, v74 quad_perm:[1,0,3,2] row_mask:0xf bank_mask:0xf bound_ctrl:1
	ds_read_b128 v[14:17], v94 offset:26912
	ds_read_b128 v[18:21], v94 offset:26928
	v_add_f32_dpp v74, v74, v74 quad_perm:[2,3,0,1] row_mask:0xf bank_mask:0xf bound_ctrl:1
	ds_read_b128 v[22:25], v94 offset:26944
	ds_write_b32 v97, v74 offset:2312
	v_mov_b32_dpp v74, v74 row_mirror row_mask:0xf bank_mask:0xc
	v_pk_fma_f32 v[2:3], v[38:39], v[74:75], v[76:77] op_sel_hi:[1,0,1]
	v_pk_fma_f32 v[4:5], v[40:41], v[74:75], v[92:93] op_sel_hi:[1,0,1]
	s_waitcnt lgkmcnt(8)
	v_pk_mul_f32 v[70:71], v[2:3], v[46:47] op_sel_hi:[0,1]
	v_pk_mul_f32 v[72:73], v[2:3], v[48:49] op_sel:[1,0]
	v_pk_fma_f32 v[70:71], v[4:5], v[50:51], v[70:71] op_sel_hi:[0,1,1]
	v_pk_fma_f32 v[72:73], v[4:5], v[52:53], v[72:73] op_sel:[1,0,0]
	v_pk_add_f32 v[70:71], v[70:71], v[72:73]
	v_pk_mul_f32 v[76:77], v[62:63], v[68:69] op_sel_hi:[1,0]
	v_pk_mul_f32 v[92:93], v[64:65], v[68:69] op_sel_hi:[1,0]
	v_add_f32_dpp v74, v71, v70 row_mirror row_mask:0xf bank_mask:0xf bound_ctrl:1
	v_pk_fma_f32 v[76:77], v[2:3], v[54:55], v[76:77]
	v_pk_fma_f32 v[92:93], v[4:5], v[56:57], v[92:93]
	v_add_f32_dpp v74, v74, v74 row_half_mirror row_mask:0xf bank_mask:0xf bound_ctrl:1
	ds_read_b128 v[26:29], v94 offset:28160
	ds_read_b128 v[30:33], v94 offset:28176
	v_add_f32_dpp v74, v74, v74 quad_perm:[1,0,3,2] row_mask:0xf bank_mask:0xf bound_ctrl:1
	ds_read_b128 v[34:37], v94 offset:28192
	ds_read_b128 v[38:41], v94 offset:28208
	v_add_f32_dpp v74, v74, v74 quad_perm:[2,3,0,1] row_mask:0xf bank_mask:0xf bound_ctrl:1
	ds_read_b128 v[42:45], v94 offset:28224
	ds_write_b32 v97, v74 offset:2560
	ds_read2_b32 v[66:67], v96 offset0:128 offset1:144
	v_mov_b32_dpp v74, v74 row_mirror row_mask:0xf bank_mask:0xc
	v_pk_fma_f32 v[2:3], v[58:59], v[74:75], v[76:77] op_sel_hi:[1,0,1]
	v_pk_fma_f32 v[4:5], v[60:61], v[74:75], v[92:93] op_sel_hi:[1,0,1]
	s_waitcnt lgkmcnt(8)
	v_pk_mul_f32 v[70:71], v[2:3], v[6:7] op_sel_hi:[0,1]
	v_pk_mul_f32 v[72:73], v[2:3], v[8:9] op_sel:[1,0]
	v_pk_fma_f32 v[70:71], v[4:5], v[10:11], v[70:71] op_sel_hi:[0,1,1]
	v_pk_fma_f32 v[72:73], v[4:5], v[12:13], v[72:73] op_sel:[1,0,0]
	v_pk_add_f32 v[70:71], v[70:71], v[72:73]
	v_pk_mul_f32 v[76:77], v[22:23], v[68:69] op_sel:[0,1]
	v_pk_mul_f32 v[92:93], v[24:25], v[68:69] op_sel:[0,1]
	v_add_f32_dpp v74, v71, v70 row_mirror row_mask:0xf bank_mask:0xf bound_ctrl:1
	v_pk_fma_f32 v[76:77], v[2:3], v[14:15], v[76:77]
	v_pk_fma_f32 v[92:93], v[4:5], v[16:17], v[92:93]
	v_add_f32_dpp v74, v74, v74 row_half_mirror row_mask:0xf bank_mask:0xf bound_ctrl:1
	ds_read_b128 v[46:49], v94 offset:29440
	ds_read_b128 v[50:53], v94 offset:29456
	v_add_f32_dpp v74, v74, v74 quad_perm:[1,0,3,2] row_mask:0xf bank_mask:0xf bound_ctrl:1
	ds_read_b128 v[54:57], v94 offset:29472
	ds_read_b128 v[58:61], v94 offset:29488
	v_add_f32_dpp v74, v74, v74 quad_perm:[2,3,0,1] row_mask:0xf bank_mask:0xf bound_ctrl:1
	ds_read_b128 v[62:65], v94 offset:29504
	ds_write_b32 v97, v74 offset:2568
	v_mov_b32_dpp v74, v74 row_mirror row_mask:0xf bank_mask:0xc
	v_pk_fma_f32 v[2:3], v[18:19], v[74:75], v[76:77] op_sel_hi:[1,0,1]
	v_pk_fma_f32 v[4:5], v[20:21], v[74:75], v[92:93] op_sel_hi:[1,0,1]
	s_waitcnt lgkmcnt(8)
	v_pk_mul_f32 v[70:71], v[2:3], v[26:27] op_sel_hi:[0,1]
	v_pk_mul_f32 v[72:73], v[2:3], v[28:29] op_sel:[1,0]
	v_pk_fma_f32 v[70:71], v[4:5], v[30:31], v[70:71] op_sel_hi:[0,1,1]
	v_pk_fma_f32 v[72:73], v[4:5], v[32:33], v[72:73] op_sel:[1,0,0]
	v_pk_add_f32 v[70:71], v[70:71], v[72:73]
	v_pk_mul_f32 v[76:77], v[42:43], v[132:133] op_sel_hi:[1,0]
	v_pk_mul_f32 v[92:93], v[44:45], v[132:133] op_sel_hi:[1,0]
	v_add_f32_dpp v74, v71, v70 row_mirror row_mask:0xf bank_mask:0xf bound_ctrl:1
	v_pk_fma_f32 v[76:77], v[2:3], v[34:35], v[76:77]
	v_pk_fma_f32 v[92:93], v[4:5], v[36:37], v[92:93]
	v_add_f32_dpp v74, v74, v74 row_half_mirror row_mask:0xf bank_mask:0xf bound_ctrl:1
	ds_read_b128 v[6:9], v94 offset:30720
	ds_read_b128 v[10:13], v94 offset:30736
	v_add_f32_dpp v74, v74, v74 quad_perm:[1,0,3,2] row_mask:0xf bank_mask:0xf bound_ctrl:1
	ds_read_b128 v[14:17], v94 offset:30752
	ds_read_b128 v[18:21], v94 offset:30768
	v_add_f32_dpp v74, v74, v74 quad_perm:[2,3,0,1] row_mask:0xf bank_mask:0xf bound_ctrl:1
	ds_read_b128 v[22:25], v94 offset:30784
	ds_write_b32 v97, v74 offset:2816
	ds_read2_b32 v[68:69], v96 offset0:160 offset1:176
	v_mov_b32_dpp v74, v74 row_mirror row_mask:0xf bank_mask:0xc
	v_pk_fma_f32 v[2:3], v[38:39], v[74:75], v[76:77] op_sel_hi:[1,0,1]
	v_pk_fma_f32 v[4:5], v[40:41], v[74:75], v[92:93] op_sel_hi:[1,0,1]
	s_waitcnt lgkmcnt(8)
	v_pk_mul_f32 v[70:71], v[2:3], v[46:47] op_sel_hi:[0,1]
	v_pk_mul_f32 v[72:73], v[2:3], v[48:49] op_sel:[1,0]
	v_pk_fma_f32 v[70:71], v[4:5], v[50:51], v[70:71] op_sel_hi:[0,1,1]
	v_pk_fma_f32 v[72:73], v[4:5], v[52:53], v[72:73] op_sel:[1,0,0]
	v_pk_add_f32 v[70:71], v[70:71], v[72:73]
	v_pk_mul_f32 v[76:77], v[62:63], v[132:133] op_sel:[0,1]
	v_pk_mul_f32 v[92:93], v[64:65], v[132:133] op_sel:[0,1]
	v_add_f32_dpp v74, v71, v70 row_mirror row_mask:0xf bank_mask:0xf bound_ctrl:1
	v_pk_fma_f32 v[76:77], v[2:3], v[54:55], v[76:77]
	v_pk_fma_f32 v[92:93], v[4:5], v[56:57], v[92:93]
	v_add_f32_dpp v74, v74, v74 row_half_mirror row_mask:0xf bank_mask:0xf bound_ctrl:1
	ds_read_b128 v[26:29], v94 offset:32000
	ds_read_b128 v[30:33], v94 offset:32016
	v_add_f32_dpp v74, v74, v74 quad_perm:[1,0,3,2] row_mask:0xf bank_mask:0xf bound_ctrl:1
	ds_read_b128 v[34:37], v94 offset:32032
	ds_read_b128 v[38:41], v94 offset:32048
	v_add_f32_dpp v74, v74, v74 quad_perm:[2,3,0,1] row_mask:0xf bank_mask:0xf bound_ctrl:1
	ds_read_b128 v[42:45], v94 offset:32064
	ds_write_b32 v97, v74 offset:2824
	v_mov_b32_dpp v74, v74 row_mirror row_mask:0xf bank_mask:0xc
	v_pk_fma_f32 v[2:3], v[58:59], v[74:75], v[76:77] op_sel_hi:[1,0,1]
	v_pk_fma_f32 v[4:5], v[60:61], v[74:75], v[92:93] op_sel_hi:[1,0,1]
	s_waitcnt lgkmcnt(8)
	v_pk_mul_f32 v[70:71], v[2:3], v[6:7] op_sel_hi:[0,1]
	v_pk_mul_f32 v[72:73], v[2:3], v[8:9] op_sel:[1,0]
	v_pk_fma_f32 v[70:71], v[4:5], v[10:11], v[70:71] op_sel_hi:[0,1,1]
	v_pk_fma_f32 v[72:73], v[4:5], v[12:13], v[72:73] op_sel:[1,0,0]
	v_pk_add_f32 v[70:71], v[70:71], v[72:73]
	v_pk_mul_f32 v[76:77], v[22:23], v[66:67] op_sel_hi:[1,0]
	v_pk_mul_f32 v[92:93], v[24:25], v[66:67] op_sel_hi:[1,0]
	v_add_f32_dpp v74, v71, v70 row_mirror row_mask:0xf bank_mask:0xf bound_ctrl:1
	v_pk_fma_f32 v[76:77], v[2:3], v[14:15], v[76:77]
	v_pk_fma_f32 v[92:93], v[4:5], v[16:17], v[92:93]
	v_add_f32_dpp v74, v74, v74 row_half_mirror row_mask:0xf bank_mask:0xf bound_ctrl:1
	ds_read_b128 v[46:49], v94 offset:33280
	ds_read_b128 v[50:53], v94 offset:33296
	v_add_f32_dpp v74, v74, v74 quad_perm:[1,0,3,2] row_mask:0xf bank_mask:0xf bound_ctrl:1
	ds_read_b128 v[54:57], v94 offset:33312
	ds_read_b128 v[58:61], v94 offset:33328
	v_add_f32_dpp v74, v74, v74 quad_perm:[2,3,0,1] row_mask:0xf bank_mask:0xf bound_ctrl:1
	ds_read_b128 v[62:65], v94 offset:33344
	ds_write_b32 v97, v74 offset:3072
	ds_read2_b32 v[132:133], v96 offset0:192 offset1:208
	v_mov_b32_dpp v74, v74 row_mirror row_mask:0xf bank_mask:0xc
	v_pk_fma_f32 v[2:3], v[18:19], v[74:75], v[76:77] op_sel_hi:[1,0,1]
	v_pk_fma_f32 v[4:5], v[20:21], v[74:75], v[92:93] op_sel_hi:[1,0,1]
	s_waitcnt lgkmcnt(8)
	v_pk_mul_f32 v[70:71], v[2:3], v[26:27] op_sel_hi:[0,1]
	v_pk_mul_f32 v[72:73], v[2:3], v[28:29] op_sel:[1,0]
	v_pk_fma_f32 v[70:71], v[4:5], v[30:31], v[70:71] op_sel_hi:[0,1,1]
	v_pk_fma_f32 v[72:73], v[4:5], v[32:33], v[72:73] op_sel:[1,0,0]
	v_pk_add_f32 v[70:71], v[70:71], v[72:73]
	v_pk_mul_f32 v[76:77], v[42:43], v[66:67] op_sel:[0,1]
	v_pk_mul_f32 v[92:93], v[44:45], v[66:67] op_sel:[0,1]
	v_add_f32_dpp v74, v71, v70 row_mirror row_mask:0xf bank_mask:0xf bound_ctrl:1
	v_pk_fma_f32 v[76:77], v[2:3], v[34:35], v[76:77]
	v_pk_fma_f32 v[92:93], v[4:5], v[36:37], v[92:93]
	v_add_f32_dpp v74, v74, v74 row_half_mirror row_mask:0xf bank_mask:0xf bound_ctrl:1
	ds_read_b128 v[6:9], v94 offset:34560
	ds_read_b128 v[10:13], v94 offset:34576
	v_add_f32_dpp v74, v74, v74 quad_perm:[1,0,3,2] row_mask:0xf bank_mask:0xf bound_ctrl:1
	ds_read_b128 v[14:17], v94 offset:34592
	ds_read_b128 v[18:21], v94 offset:34608
	v_add_f32_dpp v74, v74, v74 quad_perm:[2,3,0,1] row_mask:0xf bank_mask:0xf bound_ctrl:1
	ds_read_b128 v[22:25], v94 offset:34624
	ds_write_b32 v97, v74 offset:3080
	v_mov_b32_dpp v74, v74 row_mirror row_mask:0xf bank_mask:0xc
	v_pk_fma_f32 v[2:3], v[38:39], v[74:75], v[76:77] op_sel_hi:[1,0,1]
	v_pk_fma_f32 v[4:5], v[40:41], v[74:75], v[92:93] op_sel_hi:[1,0,1]
	s_waitcnt lgkmcnt(8)
	v_pk_mul_f32 v[70:71], v[2:3], v[46:47] op_sel_hi:[0,1]
	v_pk_mul_f32 v[72:73], v[2:3], v[48:49] op_sel:[1,0]
	v_pk_fma_f32 v[70:71], v[4:5], v[50:51], v[70:71] op_sel_hi:[0,1,1]
	v_pk_fma_f32 v[72:73], v[4:5], v[52:53], v[72:73] op_sel:[1,0,0]
	v_pk_add_f32 v[70:71], v[70:71], v[72:73]
	v_pk_mul_f32 v[76:77], v[62:63], v[68:69] op_sel_hi:[1,0]
	v_pk_mul_f32 v[92:93], v[64:65], v[68:69] op_sel_hi:[1,0]
	v_add_f32_dpp v74, v71, v70 row_mirror row_mask:0xf bank_mask:0xf bound_ctrl:1
	v_pk_fma_f32 v[76:77], v[2:3], v[54:55], v[76:77]
	v_pk_fma_f32 v[92:93], v[4:5], v[56:57], v[92:93]
	v_add_f32_dpp v74, v74, v74 row_half_mirror row_mask:0xf bank_mask:0xf bound_ctrl:1
	ds_read_b128 v[26:29], v94 offset:35840
	ds_read_b128 v[30:33], v94 offset:35856
	v_add_f32_dpp v74, v74, v74 quad_perm:[1,0,3,2] row_mask:0xf bank_mask:0xf bound_ctrl:1
	ds_read_b128 v[34:37], v94 offset:35872
	ds_read_b128 v[38:41], v94 offset:35888
	v_add_f32_dpp v74, v74, v74 quad_perm:[2,3,0,1] row_mask:0xf bank_mask:0xf bound_ctrl:1
	ds_read_b128 v[42:45], v94 offset:35904
	ds_write_b32 v97, v74 offset:3328
	ds_read2_b32 v[66:67], v96 offset0:224 offset1:240
	v_mov_b32_dpp v74, v74 row_mirror row_mask:0xf bank_mask:0xc
	v_pk_fma_f32 v[2:3], v[58:59], v[74:75], v[76:77] op_sel_hi:[1,0,1]
	v_pk_fma_f32 v[4:5], v[60:61], v[74:75], v[92:93] op_sel_hi:[1,0,1]
	s_waitcnt lgkmcnt(8)
	v_pk_mul_f32 v[70:71], v[2:3], v[6:7] op_sel_hi:[0,1]
	v_pk_mul_f32 v[72:73], v[2:3], v[8:9] op_sel:[1,0]
	v_pk_fma_f32 v[70:71], v[4:5], v[10:11], v[70:71] op_sel_hi:[0,1,1]
	v_pk_fma_f32 v[72:73], v[4:5], v[12:13], v[72:73] op_sel:[1,0,0]
	v_pk_add_f32 v[70:71], v[70:71], v[72:73]
	v_pk_mul_f32 v[76:77], v[22:23], v[68:69] op_sel:[0,1]
	v_pk_mul_f32 v[92:93], v[24:25], v[68:69] op_sel:[0,1]
	v_add_f32_dpp v74, v71, v70 row_mirror row_mask:0xf bank_mask:0xf bound_ctrl:1
	v_pk_fma_f32 v[76:77], v[2:3], v[14:15], v[76:77]
	v_pk_fma_f32 v[92:93], v[4:5], v[16:17], v[92:93]
	v_add_f32_dpp v74, v74, v74 row_half_mirror row_mask:0xf bank_mask:0xf bound_ctrl:1
	ds_read_b128 v[46:49], v94 offset:37120
	ds_read_b128 v[50:53], v94 offset:37136
	v_add_f32_dpp v74, v74, v74 quad_perm:[1,0,3,2] row_mask:0xf bank_mask:0xf bound_ctrl:1
	ds_read_b128 v[54:57], v94 offset:37152
	ds_read_b128 v[58:61], v94 offset:37168
	v_add_f32_dpp v74, v74, v74 quad_perm:[2,3,0,1] row_mask:0xf bank_mask:0xf bound_ctrl:1
	ds_read_b128 v[62:65], v94 offset:37184
	ds_write_b32 v97, v74 offset:3336
	v_mov_b32_dpp v74, v74 row_mirror row_mask:0xf bank_mask:0xc
	v_pk_fma_f32 v[2:3], v[18:19], v[74:75], v[76:77] op_sel_hi:[1,0,1]
	v_pk_fma_f32 v[4:5], v[20:21], v[74:75], v[92:93] op_sel_hi:[1,0,1]
	s_waitcnt lgkmcnt(8)
	v_pk_mul_f32 v[70:71], v[2:3], v[26:27] op_sel_hi:[0,1]
	v_pk_mul_f32 v[72:73], v[2:3], v[28:29] op_sel:[1,0]
	v_pk_fma_f32 v[70:71], v[4:5], v[30:31], v[70:71] op_sel_hi:[0,1,1]
	v_pk_fma_f32 v[72:73], v[4:5], v[32:33], v[72:73] op_sel:[1,0,0]
	v_pk_add_f32 v[70:71], v[70:71], v[72:73]
	v_pk_mul_f32 v[76:77], v[42:43], v[132:133] op_sel_hi:[1,0]
	v_pk_mul_f32 v[92:93], v[44:45], v[132:133] op_sel_hi:[1,0]
	v_add_f32_dpp v74, v71, v70 row_mirror row_mask:0xf bank_mask:0xf bound_ctrl:1
	v_pk_fma_f32 v[76:77], v[2:3], v[34:35], v[76:77]
	v_pk_fma_f32 v[92:93], v[4:5], v[36:37], v[92:93]
	v_add_f32_dpp v74, v74, v74 row_half_mirror row_mask:0xf bank_mask:0xf bound_ctrl:1
	ds_read_b128 v[6:9], v94 offset:38400
	ds_read_b128 v[10:13], v94 offset:38416
	v_add_f32_dpp v74, v74, v74 quad_perm:[1,0,3,2] row_mask:0xf bank_mask:0xf bound_ctrl:1
	ds_read_b128 v[14:17], v94 offset:38432
	ds_read_b128 v[18:21], v94 offset:38448
	v_add_f32_dpp v74, v74, v74 quad_perm:[2,3,0,1] row_mask:0xf bank_mask:0xf bound_ctrl:1
	ds_read_b128 v[22:25], v94 offset:38464
	ds_write_b32 v97, v74 offset:3584
	v_mov_b32_dpp v74, v74 row_mirror row_mask:0xf bank_mask:0xc
	v_pk_fma_f32 v[2:3], v[38:39], v[74:75], v[76:77] op_sel_hi:[1,0,1]
	v_pk_fma_f32 v[4:5], v[40:41], v[74:75], v[92:93] op_sel_hi:[1,0,1]
	s_waitcnt lgkmcnt(7)
	v_pk_mul_f32 v[70:71], v[2:3], v[46:47] op_sel_hi:[0,1]
	v_pk_mul_f32 v[72:73], v[2:3], v[48:49] op_sel:[1,0]
	v_pk_fma_f32 v[70:71], v[4:5], v[50:51], v[70:71] op_sel_hi:[0,1,1]
	v_pk_fma_f32 v[72:73], v[4:5], v[52:53], v[72:73] op_sel:[1,0,0]
	v_pk_add_f32 v[70:71], v[70:71], v[72:73]
	v_pk_mul_f32 v[76:77], v[62:63], v[132:133] op_sel:[0,1]
	v_pk_mul_f32 v[92:93], v[64:65], v[132:133] op_sel:[0,1]
	v_add_f32_dpp v74, v71, v70 row_mirror row_mask:0xf bank_mask:0xf bound_ctrl:1
	v_pk_fma_f32 v[76:77], v[2:3], v[54:55], v[76:77]
	v_pk_fma_f32 v[92:93], v[4:5], v[56:57], v[92:93]
	v_add_f32_dpp v74, v74, v74 row_half_mirror row_mask:0xf bank_mask:0xf bound_ctrl:1
	ds_read_b128 v[26:29], v94 offset:39680
	ds_read_b128 v[30:33], v94 offset:39696
	v_add_f32_dpp v74, v74, v74 quad_perm:[1,0,3,2] row_mask:0xf bank_mask:0xf bound_ctrl:1
	ds_read_b128 v[34:37], v94 offset:39712
	ds_read_b128 v[38:41], v94 offset:39728
	v_add_f32_dpp v74, v74, v74 quad_perm:[2,3,0,1] row_mask:0xf bank_mask:0xf bound_ctrl:1
	ds_read_b128 v[42:45], v94 offset:39744
	ds_write_b32 v97, v74 offset:3592
	v_mov_b32_dpp v74, v74 row_mirror row_mask:0xf bank_mask:0xc
	v_pk_fma_f32 v[2:3], v[58:59], v[74:75], v[76:77] op_sel_hi:[1,0,1]
	v_pk_fma_f32 v[4:5], v[60:61], v[74:75], v[92:93] op_sel_hi:[1,0,1]
	s_waitcnt lgkmcnt(7)
	v_pk_mul_f32 v[70:71], v[2:3], v[6:7] op_sel_hi:[0,1]
	v_pk_mul_f32 v[72:73], v[2:3], v[8:9] op_sel:[1,0]
	v_pk_fma_f32 v[70:71], v[4:5], v[10:11], v[70:71] op_sel_hi:[0,1,1]
	v_pk_fma_f32 v[72:73], v[4:5], v[12:13], v[72:73] op_sel:[1,0,0]
	v_pk_add_f32 v[70:71], v[70:71], v[72:73]
	v_pk_mul_f32 v[76:77], v[22:23], v[66:67] op_sel_hi:[1,0]
	v_pk_mul_f32 v[92:93], v[24:25], v[66:67] op_sel_hi:[1,0]
	v_add_f32_dpp v74, v71, v70 row_mirror row_mask:0xf bank_mask:0xf bound_ctrl:1
	v_pk_fma_f32 v[76:77], v[2:3], v[14:15], v[76:77]
	v_pk_fma_f32 v[92:93], v[4:5], v[16:17], v[92:93]
	v_add_f32_dpp v74, v74, v74 row_half_mirror row_mask:0xf bank_mask:0xf bound_ctrl:1
	s_nop 1
	v_add_f32_dpp v74, v74, v74 quad_perm:[1,0,3,2] row_mask:0xf bank_mask:0xf bound_ctrl:1
	s_nop 1
	v_add_f32_dpp v74, v74, v74 quad_perm:[2,3,0,1] row_mask:0xf bank_mask:0xf bound_ctrl:1
	s_nop 0
	ds_write_b32 v97, v74 offset:3840
	v_mov_b32_dpp v74, v74 row_mirror row_mask:0xf bank_mask:0xc
	v_pk_fma_f32 v[2:3], v[18:19], v[74:75], v[76:77] op_sel_hi:[1,0,1]
	v_pk_fma_f32 v[4:5], v[20:21], v[74:75], v[92:93] op_sel_hi:[1,0,1]
	s_waitcnt lgkmcnt(2)
	v_pk_mul_f32 v[70:71], v[2:3], v[26:27] op_sel_hi:[0,1]
	v_pk_mul_f32 v[72:73], v[2:3], v[28:29] op_sel:[1,0]
	v_pk_fma_f32 v[70:71], v[4:5], v[30:31], v[70:71] op_sel_hi:[0,1,1]
	v_pk_fma_f32 v[72:73], v[4:5], v[32:33], v[72:73] op_sel:[1,0,0]
	v_pk_add_f32 v[70:71], v[70:71], v[72:73]
	v_pk_mul_f32 v[76:77], v[42:43], v[66:67] op_sel:[0,1]
	v_pk_mul_f32 v[92:93], v[44:45], v[66:67] op_sel:[0,1]
	v_add_f32_dpp v74, v71, v70 row_mirror row_mask:0xf bank_mask:0xf bound_ctrl:1
	v_pk_fma_f32 v[76:77], v[2:3], v[34:35], v[76:77]
	v_pk_fma_f32 v[92:93], v[4:5], v[36:37], v[92:93]
	v_add_f32_dpp v74, v74, v74 row_half_mirror row_mask:0xf bank_mask:0xf bound_ctrl:1
	s_nop 1
	v_add_f32_dpp v74, v74, v74 quad_perm:[1,0,3,2] row_mask:0xf bank_mask:0xf bound_ctrl:1
	s_nop 1
	v_add_f32_dpp v74, v74, v74 quad_perm:[2,3,0,1] row_mask:0xf bank_mask:0xf bound_ctrl:1
	s_nop 0
	ds_write_b32 v97, v74 offset:3848
	v_mov_b32_dpp v74, v74 row_mirror row_mask:0xf bank_mask:0xc
	v_pk_fma_f32 v[2:3], v[38:39], v[74:75], v[76:77] op_sel_hi:[1,0,1]
	v_pk_fma_f32 v[4:5], v[40:41], v[74:75], v[92:93] op_sel_hi:[1,0,1]
	s_add_i32 s33, s33, 1
	s_cmpk_lg_i32 s33, 0x80
	s_waitcnt lgkmcnt(0)
	s_barrier
	s_cbranch_scc1 .Lscan_chunk
	s_setprio 0
